# P1 GEMM: half of the workgroups (bit 3 of block index) start 2x s_sleep 127 later to interleave epilogue store bursts
# speedup vs baseline: 1.0027x; 1.0027x over previous
; #define PG8_STAGE(bufoff, gbase, voff) do { _Pragma("unroll") for (int _i = 0; _i < 2; ++_i) \
;         __builtin_amdgcn_global_load_lds((const unsigned*)((const char*)(gbase) + (voff)[_i]), (PG8_LAS unsigned*)(lds + (bufoff) + ldsw + _i * 8192), 16, 0, 0); } while (0)
; #define PG8_WAIT_V(n) asm volatile("s_waitcnt vmcnt(" #n ")" ::: "memory")
; #define PG8_BAR __builtin_amdgcn_s_barrier()
; template <class Epi, class Sched, bool ALIGN_EPI = false, bool SP2 = false>
; __device__ __forceinline__ void gemm_phase(PG8_LAS unsigned char* lds, const Gemm g, const Sched& S, const Epi& E) {
;     ...
;     for (int i = 0; i < 2; ++i) { int R, C; stage_rc(tid * 16 + i * 8192, R, C); const int Rb = Epi::PERM ? ((R & ~31) + perm32(R & 31)) : R;
;         voffA[i] = (unsigned)(R * K + C) * 2u; voffB[i] = (unsigned)(Rb * K + C) * 2u; }
;     const size_t kstep = (size_t)(BK * 2);
;     const size_t hstep = (size_t)HALF * K * 2;
;     const size_t tstep = 2 * hstep;
;     const unsigned ldsw = (unsigned)wid * 1024u;
;     const int aoff = lds_byte(wr * 64 + fr, fq * 8), boff = lds_byte(wc * 32 + fr, fq * 8);
;     ...
;     Unit cur, nxt; int ui = 0;
;     if (!S.next(0, cur)) return;
;     f32x4 acc[2][2][4][2];
; #pragma unroll
;     for (int a = 0; a < 2; ++a)
; #pragma unroll
;         for (int b = 0; b < 2; ++b)
; #pragma unroll
;             for (int m = 0; m < 4; ++m)
; #pragma unroll
;                 for (int n = 0; n < 2; ++n) acc[a][b][m][n] = (f32x4){0.f, 0.f, 0.f, 0.f};
;     bf16x8 At[4][2], B0[2][2], B1[2][2];
;     const char* cA = (const char*)g.A + (size_t)cur.pm * tstep; const char* cB = (const char*)g.Bt + (size_t)cur.pn * tstep;
;     S.a_ready(cur);
;     if constexpr (SP2) {
;         PG8_STAGE(PG8_SB(0, 0), cB, voffB); PG8_STAGE(PG8_SB(0, 1), cB + hstep, voffB); PG8_STAGE(PG8_SA(0, 0), cA, voffA); PG8_STAGE(PG8_SA(0, 1), cA + hstep, voffA);
;         if (wr == 1) PG8_BAR;
;         PG8_WAIT_V(2); PG8_BAR;
;         PG8_STAGE(PG8_SB(1, 0), cB + kstep, voffB); PG8_STAGE(PG8_SA(1, 0), cA + kstep, voffA); PG8_STAGE(PG8_SB(1, 1), cB + hstep + kstep, voffB);
;         PG8_WAIT_V(6); PG8_BAR;
;     } else {
;         PG8_STAGE(PG8_SB(0, 0), cB, voffB); PG8_STAGE(PG8_SA(0, 0), cA, voffA); PG8_STAGE(PG8_SB(0, 1), cB + hstep, voffB); PG8_STAGE(PG8_SA(0, 1), cA + hstep, voffA);
.LBB0_93:
	s_andn2_b64 vcc, exec, s[6:7]
	s_cbranch_vccnz .LBB0_162
	s_bitcmp1_b32 s2, 3
	s_cbranch_scc0 .Lp1_nostag
	s_sleep 127
	s_sleep 127
.Lp1_nostag:
	v_lshrrev_b32_e32 v3, 1, v0
	v_and_b32_e32 v13, 24, v3
	v_lshrrev_b32_e32 v3, 5, v0
	v_lshlrev_b32_e32 v1, 4, v0
	v_and_b32_e32 v2, 32, v0
	v_and_b32_e32 v3, 4, v3
	v_bfe_u32 v4, v0, 2, 2
	v_bfe_u32 v12, v0, 2, 4
	v_bitop3_b32 v10, v1, v2, 48 bitop3:0x6c
	v_and_b32_e32 v11, 64, v0
	v_or3_b32 v3, v3, v4, v13
	v_lshrrev_b32_e32 v4, 3, v0
	v_or_b32_e32 v14, 0x2000, v1
	v_or_b32_e32 v2, v10, v11
	v_and_or_b32 v5, v4, 48, v12
	v_and_or_b32 v4, v4, 32, v3
	v_lshrrev_b32_e32 v1, 7, v14
	s_movk_i32 s5, 0x70
	s_add_u32 s74, s28, 0x400000
	v_lshl_or_b32 v132, v4, 11, v2
	v_and_or_b32 v4, v1, s5, v12
	s_movk_i32 s5, 0x60
	s_addc_u32 s75, s29, 0
	v_and_or_b32 v1, v1, s5, v3
	s_lshr_b32 s7, s12, 6
	s_ashr_i32 s5, s4, 31
	s_ashr_i32 s65, s64, 31
	s_lshr_b32 s6, s12, 8
	s_lshl_b32 s76, s7, 10
	s_lshl_b64 s[8:9], s[4:5], 19
	s_lshl_b64 s[10:11], s[64:65], 19
	s_add_u32 s68, s74, s10
	s_addc_u32 s69, s75, s11
	s_add_i32 s65, s76, 0
	s_add_i32 m0, s65, 0x10000
	v_lshl_or_b32 v136, v1, 11, v2
	global_load_lds_dwordx4 v132, s[68:69]
	s_add_i32 m0, s65, 0x12000
	s_add_u32 s10, s68, 0x40000
	global_load_lds_dwordx4 v136, s[68:69]
	s_addc_u32 s11, s69, 0
	s_add_i32 m0, s65, 0x14000
	v_lshl_or_b32 v130, v5, 11, v2
	global_load_lds_dwordx4 v132, s[10:11]
	s_add_i32 m0, s65, 0x16000
	s_add_u32 s66, s26, s8
	s_addc_u32 s67, s27, s9
	s_add_i32 s77, s65, 0x2000
	global_load_lds_dwordx4 v136, s[10:11]
	s_mov_b32 m0, s65
	s_add_u32 s8, s66, 0x40000
	v_lshl_or_b32 v134, v4, 11, v2
	global_load_lds_dwordx4 v130, s[66:67]
	s_mov_b32 m0, s77
	s_addc_u32 s9, s67, 0
	s_add_i32 s78, s65, 0x4000
	global_load_lds_dwordx4 v134, s[66:67]
	s_mov_b32 m0, s78
	s_add_i32 s79, s65, 0x6000
	global_load_lds_dwordx4 v130, s[8:9]
	s_mov_b32 m0, s79
	v_mov_b32_e32 v139, 0
	global_load_lds_dwordx4 v134, s[8:9]
	v_mov_b32_e32 v133, v139
	v_mov_b32_e32 v137, v139
	v_mov_b32_e32 v131, v139
	v_mov_b32_e32 v135, v139
	s_cmp_eq_u32 s6, 1
	s_mov_b32 s80, 0
	v_lshl_add_u64 v[8:9], s[68:69], 0, v[132:133]
	v_lshl_add_u64 v[6:7], s[68:69], 0, v[136:137]
	v_lshl_add_u64 v[2:3], s[66:67], 0, v[130:131]
	s_cselect_b64 s[8:9], -1, 0
	s_cmp_lg_u32 s6, 1
	v_lshl_add_u64 v[4:5], s[66:67], 0, v[134:135]
	s_cbranch_scc1 .LBB0_96
	s_barrier
